# v17 rebuilt with common-subexpression reuse in the pass A preheader (636 -> 401 one-time instructions)
# speedup vs baseline: 1.0055x; 1.0055x over previous
.LBB0_661:
	v_writelane_b32 v233, s72, 28
	s_add_u32 s10, s86, 0x16b00000
	s_addc_u32 s11, s87, 0
	v_writelane_b32 v233, s73, 29
	v_writelane_b32 v233, s57, 30
	v_writelane_b32 v233, s71, 31
	s_add_u32 s0, s86, 0x1cd00000
	v_writelane_b32 v233, s0, 32
	s_addc_u32 s0, s87, 0
	v_writelane_b32 v233, s0, 33
	s_add_u32 s0, s84, 0x2000000
	s_addc_u32 s1, s85, 0
	s_add_u32 s50, s86, 0x1f700000
	v_writelane_b32 v233, s0, 34
	s_addc_u32 s51, s87, 0
	s_mov_b32 s73, 0x5040100
	v_writelane_b32 v233, s1, 35
	s_add_u32 s0, s86, 0x1f800000
	s_addc_u32 s1, s87, 0
	v_writelane_b32 v233, s0, 36
	s_ashr_i32 s71, s70, 31
	s_mov_b64 s[42:43], s[70:71]
	v_writelane_b32 v233, s1, 37
	s_ashr_i32 s0, s41, 31
	v_writelane_b32 v233, s0, 38
	s_lshl_b32 s0, s42, 5
	v_readlane_b32 s13, v233, 5
	s_and_b32 s15, s0, 0x60
	s_lshl_b32 s0, s13, 8
	s_add_i32 s48, 0, 0x12000
	s_ashr_i32 s14, s70, 3
	s_add_i32 s49, s48, s0
	s_cmp_lt_u32 s74, 64
	s_cselect_b64 s[24:25], -1, 0
	s_cmp_gt_u32 s74, 63
	s_cselect_b64 s[26:27], -1, 0
	s_cmpk_gt_u32 s74, 0x7f
	s_cselect_b64 s[0:1], -1, 0
	v_writelane_b32 v233, s0, 39
	s_cmpk_gt_u32 s74, 0xbf
	s_mul_i32 s4, s13, 0x480
	v_writelane_b32 v233, s1, 40
	s_cselect_b64 s[0:1], -1, 0
	v_writelane_b32 v233, s0, 41
	s_cmpk_gt_u32 s74, 0xff
	v_mov_b32_e32 v3, 0
	v_writelane_b32 v233, s1, 42
	s_cselect_b64 s[0:1], -1, 0
	v_writelane_b32 v233, s0, 43
	s_cmpk_gt_u32 s74, 0x13f
	s_waitcnt vmcnt(0)
	v_perm_b32 v88, v47, v0, s73
	v_writelane_b32 v233, s1, 44
	s_cselect_b64 s[0:1], -1, 0
	v_writelane_b32 v233, s0, 45
	s_cmpk_gt_u32 s74, 0x17f
	v_mov_b32_e32 v77, 0x260
	v_writelane_b32 v233, s1, 46
	s_cselect_b64 s[0:1], -1, 0
	v_writelane_b32 v233, s0, 47
	s_cmpk_gt_u32 s74, 0x1bf
	s_movk_i32 s76, 0x90
	v_writelane_b32 v233, s1, 48
	s_cselect_b64 s[0:1], -1, 0
	v_writelane_b32 v233, s0, 49
	s_cmpk_gt_u32 s74, 0x1ff
	v_mov_b64_e32 v[20:21], 0x1000
	v_writelane_b32 v233, s1, 50
	s_cselect_b64 s[0:1], -1, 0
	s_lshl_b32 s88, s13, 4
	v_writelane_b32 v233, s0, 51
	s_add_i32 s53, s88, 0
	s_lshr_b32 s5, s74, 7
	s_bfe_u32 s6, s74, 0x10006
	v_writelane_b32 v233, s1, 52
	s_cmpk_lt_u32 s74, 0x100
	s_mov_b32 s1, 0x9000
	s_cselect_b32 s0, 0, 0x2400
	s_cselect_b32 s7, s1, 0x1ce00
	s_movk_i32 s1, 0x4800
	s_cselect_b32 s8, s1, 0x6c00
	s_add_i32 s54, s0, 0
	s_bitcmp0_b32 s74, 7
	s_cselect_b32 s0, s1, 0x6c00
	s_add_i32 s55, s0, 0
	s_lshl_b32 s9, s6, 1
	s_cmpk_lt_u32 s74, 0x80
	s_cselect_b64 s[28:29], -1, 0
	s_cmp_eq_u32 s5, 2
	s_mov_b32 s0, 0x17200
	s_cselect_b32 s12, s0, 0x19600
	s_cmp_eq_u32 s5, 1
	s_cselect_b64 s[20:21], -1, 0
	s_and_b64 s[0:1], s[20:21], exec
	s_cselect_b32 s0, 0x14e00, s12
	s_add_i32 s56, s0, 0
	s_lshl_b32 s57, s6, 5
	s_lshl_b32 s58, s6, 6
	s_and_b32 s0, 64, s74
	s_cmp_eq_u32 s6, 0
	s_cselect_b64 s[30:31], -1, 0
	s_cmp_lg_u32 s0, 0
	s_cselect_b64 s[34:35], -1, 0
	s_or_b32 s62, s9, 1
	s_lshl_b32 s60, s62, 4
	s_lshl_b32 s61, s62, 5
	s_cmp_lg_u32 s13, 1
	s_mul_i32 s0, s13, 0x300
	s_cselect_b64 s[36:37], -1, 0
	s_add_i32 s64, s0, 0
	s_sub_i32 s63, s88, 64
	s_add_i32 s64, s64, 0x1ba00
	s_lshl_b32 s65, s13, 5
	s_cmpk_lt_u32 s74, 0xc0
	v_writelane_b32 v233, s74, 53
	s_cselect_b64 s[38:39], -1, 0
	s_add_i32 s0, s88, 16
	v_writelane_b32 v233, s0, 54
	s_lshl_b32 s0, s6, 3
	s_add_i32 s71, s0, 0
	s_lshl_b32 s0, s42, 9
	s_and_b32 s0, s0, 0x800
	v_writelane_b32 v233, s14, 56
	s_add_i32 s0, s14, s0
	v_writelane_b32 v233, s15, 57
	s_add_i32 s75, s0, s15
	s_load_dwordx2 s[40:41], s[82:83], 0x58
	s_load_dwordx4 s[12:15], s[82:83], 0x88
	s_lshl_b32 s69, s63, 1
	s_add_i32 s70, s69, 0
	s_lshl_b32 s1, s5, 6
	v_cndmask_b32_e64 v69, 0, 1, s[20:21]
	s_mul_i32 s59, s6, 0xa00
	s_mulk_i32 s62, 0x500
	s_add_i32 s66, s7, 0
	s_add_i32 s67, s8, 0
	s_and_b32 s68, s88, 48
	s_add_i32 s70, s70, 0x1ce00
	s_add_i32 s71, s71, s1
	s_add_i32 s72, s48, s65
	s_add_i32 s74, s4, 0
	s_add_i32 s77, 0, 0xfc00
	v_mov_b32_e32 v78, 0xf800000
	v_mov_b32_e32 v79, 0x4f800000
	v_mov_b32_e32 v124, v3
	v_mov_b32_e32 v125, v3
	v_mov_b32_e32 v80, 0x1e800
	v_mov_b32_e32 v81, 0x14400
	v_mov_b32_e32 v82, 0x900
	v_mov_b32_e32 v83, 0x1200
	v_mov_b32_e32 v87, 0x1b00
	s_mov_b32 s78, 0
	v_writelane_b32 v233, s42, 58
	s_mov_b32 s16, 0
	s_nop 0
	v_writelane_b32 v233, s43, 59
	v_mov_b32_e32 v213, v23
	v_ashrrev_i32_e32 v214, 3, v213
	v_add_u32_e32 v215, s33, v214
	v_mul_lo_u32 v216, v215, s76
	v_lshlrev_b32_e32 v217, 4, v213
	v_and_b32_e32 v218, 0x70, v217
	v_add3_u32 v130, 0, v216, v218
	v_and_b32_e32 v219, 0xffffff0, v213
	v_mul_lo_u32 v220, v219, s76
	v_lshlrev_b32_e32 v221, 1, v213
	v_add3_u32 v131, 0, v220, v221
	v_mov_b32_e32 v213, v23
	v_and_b32_e32 v214, 15, v213
	v_or_b32_e32 v215, s63, v214
	v_mul_lo_u32 v216, v215, s76
	v_and_b32_e32 v217, -16, v213
	v_add3_u32 v132, 0, v216, v217
	s_add_i32 s90, 0, 0x14e00
	v_ashrrev_i32_e32 v218, 3, v213
	v_add_u32_e32 v219, s33, v218
	v_mul_lo_u32 v220, v219, s76
	v_lshlrev_b32_e32 v221, 4, v213
	v_and_b32_e32 v222, 0x70, v221
	v_add3_u32 v133, s90, v220, v222
	s_add_i32 s91, 0, 0x14e00
	v_mov_b32_e32 v213, v23
	v_and_b32_e32 v214, 15, v213
	v_mul_u32_u24_e32 v215, 0x90, v214
	v_and_b32_e32 v216, -16, v213
	v_add3_u32 v134, s91, v215, v216
	s_add_i32 s92, 0, 0x1ba00
	v_ashrrev_i32_e32 v217, 4, v213
	s_movk_i32 s93, 0x300
	v_mul_lo_u32 v218, v217, s93
	v_mul_u32_u24_e32 v219, 48, v214
	v_add3_u32 v135, s92, v218, v219
	s_add_i32 s94, 0, 0x1ce00
	v_ashrrev_i32_e32 v220, 3, v213
	v_add_u32_e32 v221, s33, v220
	v_mul_lo_u32 v222, v221, s76
	v_lshlrev_b32_e32 v223, 4, v213
	v_and_b32_e32 v224, 0x70, v223
	v_add3_u32 v136, s94, v222, v224
	s_add_i32 s95, 0, 0x1ce00
	v_mov_b32_e32 v213, v23
	v_and_b32_e32 v214, 15, v213
	v_or_b32_e32 v215, s63, v214
	v_mul_lo_u32 v216, v215, s76
	v_ashrrev_i32_e32 v217, 4, v213
	v_lshlrev_b32_e32 v218, 3, v217
	v_add3_u32 v138, s95, v216, v218
	v_ashrrev_i32_e32 v219, 3, v213
	v_add_u32_e32 v220, s33, v219
	v_mul_lo_u32 v221, v220, s76
	v_lshlrev_b32_e32 v222, 4, v213
	v_and_b32_e32 v223, 0x70, v222
	v_add3_u32 v139, s48, v221, v223
	v_mov_b32_e32 v213, v23
	v_and_b32_e32 v214, 15, v213
	v_or_b32_e32 v215, s57, v214
	v_mul_u32_u24_e32 v216, 0x90, v215
	v_and_b32_e32 v217, -16, v213
	v_add3_u32 v140, s54, v216, v217
	v_or_b32_e32 v218, s60, v214
	v_mul_u32_u24_e32 v219, 0x90, v218
	v_add3_u32 v141, s54, v219, v217
	v_mul_u32_u24_e32 v220, 0x90, v214
	v_add_u32_e32 v221, 0x1200, v220
	v_add3_u32 v142, s55, v221, v217
	v_mov_b32_e32 v213, v23
	v_and_b32_e32 v214, 15, v213
	v_mul_u32_u24_e32 v215, 0x90, v214
	v_add_u32_e32 v216, 0x900, v215
	v_and_b32_e32 v217, -16, v213
	v_add3_u32 v143, s55, v216, v217
	v_or_b32_e32 v218, 16, v214
	v_mul_u32_u24_e32 v219, 0x90, v218
	v_add3_u32 v144, s55, v219, v217
	v_or_b32_e32 v220, 32, v214
	v_mul_u32_u24_e32 v221, 0x90, v220
	v_add3_u32 v145, s55, v221, v217
	v_mov_b32_e32 v213, v23
	v_and_b32_e32 v214, 15, v213
	v_or_b32_e32 v215, 48, v214
	v_mul_u32_u24_e32 v216, 0x90, v215
	v_and_b32_e32 v217, -16, v213
	v_add3_u32 v146, s55, v216, v217
	v_mul_lo_u32 v218, v213, s76
	v_add_u32_e32 v147, 0, v218
	v_lshlrev_b32_e32 v219, 2, v213
	v_add_u32_e32 v220, 0, v219
	v_add_u32_e32 v148, 0x12000, v220
	v_mov_b32_e32 v213, v23
	v_and_b32_e32 v214, 15, v213
	v_mul_u32_u24_e32 v215, 0x50, v214
	v_and_b32_e32 v216, -16, v213
	v_add3_u32 v217, 0, v215, v216
	v_add_u32_e32 v218, s59, v217
	v_add_u32_e32 v149, 0x14400, v218
	v_add_u32_e32 v150, 0x1e800, v218
	v_ashrrev_i32_e32 v219, 4, v213
	v_lshlrev_b32_e32 v220, 3, v219
	v_add_u32_e32 v221, s56, v220
	v_or_b32_e32 v222, s57, v214
	v_mul_u32_u24_e32 v223, 0x90, v222
	v_add_u32_e32 v151, v221, v223
	v_mov_b32_e32 v213, v23
	v_ashrrev_i32_e32 v214, 4, v213
	v_lshlrev_b32_e32 v215, 3, v214
	v_add_u32_e32 v216, s56, v215
	v_and_b32_e32 v217, 15, v213
	v_or_b32_e32 v218, s60, v217
	v_mul_u32_u24_e32 v219, 0x90, v218
	v_add_u32_e32 v152, v216, v219
	v_add_u32_e32 v220, s48, v215
	v_add_u32_e32 v221, s58, v220
	v_mul_u32_u24_e32 v222, 0x90, v217
	v_add_u32_e32 v223, 0x1200, v222
	v_add_u32_e32 v153, v221, v223
	v_mov_b32_e32 v213, v23
	v_ashrrev_i32_e32 v214, 4, v213
	v_lshlrev_b32_e32 v215, 3, v214
	v_add_u32_e32 v216, s48, v215
	v_add_u32_e32 v217, s58, v216
	v_and_b32_e32 v218, 15, v213
	v_mul_u32_u24_e32 v219, 0x90, v218
	v_add_u32_e32 v220, 0x900, v219
	v_add_u32_e32 v154, v217, v220
	v_mov_b32_e32 v213, v23
	v_ashrrev_i32_e32 v214, 4, v213
	v_lshlrev_b32_e32 v215, 3, v214
	v_add_u32_e32 v216, s48, v215
	v_add_u32_e32 v217, s58, v216
	v_and_b32_e32 v218, 15, v213
	v_mul_u32_u24_e32 v219, 0x90, v218
	v_add_u32_e32 v155, v217, v219
	v_mov_b32_e32 v220, s55
	v_mad_u32_u24 v221, v218, s76, v220
	v_and_b32_e32 v222, -16, v213
	v_add_u32_e32 v156, v221, v222
	v_mov_b32_e32 v213, v23
	v_lshlrev_b32_e32 v214, 2, v213
	v_add_u32_e32 v158, s49, v214
	v_mul_lo_u32 v215, v213, s76
	v_add_u32_e32 v159, s53, v215
	v_and_b32_e32 v160, -16, v213
	v_and_b32_e32 v161, 15, v213
	v_ashrrev_i32_e32 v162, 4, v213
	v_lshlrev_b32_e32 v216, 2, v162
	v_add_u32_e32 v217, 16, v216
	v_or_b32_e32 v218, s60, v161
	v_cmp_le_i32_e32 vcc, v217, v218
	s_nop 1
	v_cndmask_b32_e64 v219, 0, 1, vcc
	v_cmp_lt_i32_e32 vcc, v217, v218
	s_nop 1
	v_cndmask_b32_e64 v220, 0, 1, vcc
	v_cndmask_b32_e64 v221, v219, v220, s[20:21]
	v_and_b32_e32 v222, 1, v221
	v_cmp_eq_u32_e32 vcc, 1, v222
	s_nop 1
	v_cndmask_b32_e64 v163, 0, -1, vcc
	v_lshlrev_b32_e32 v213, 2, v162
	v_add_u32_e32 v214, 17, v213
	v_or_b32_e32 v215, s60, v161
	v_cmp_le_i32_e32 vcc, v214, v215
	s_nop 1
	v_cndmask_b32_e64 v216, 0, 1, vcc
	v_cmp_lt_i32_e32 vcc, v214, v215
	s_nop 1
	v_cndmask_b32_e64 v217, 0, 1, vcc
	v_cndmask_b32_e64 v218, v216, v217, s[20:21]
	v_and_b32_e32 v219, 1, v218
	v_cmp_eq_u32_e32 vcc, 1, v219
	s_nop 1
	v_cndmask_b32_e64 v164, 0, -1, vcc
	v_cmp_gt_i32_e32 vcc, 2, v162
	s_nop 1
	v_cndmask_b32_e64 v165, 0, -1, vcc
	v_or_b32_e32 v220, s57, v161
	v_or_b32_e32 v221, v213, v69
	v_cmp_gt_i32_e32 vcc, v220, v221
	s_nop 1
	v_cndmask_b32_e64 v166, 0, -1, vcc
	v_or_b32_e32 v213, s60, v161
	v_lshlrev_b32_e32 v214, 2, v162
	v_or_b32_e32 v215, v214, v69
	v_cmp_gt_i32_e32 vcc, v213, v215
	s_nop 1
	v_cndmask_b32_e64 v167, 0, -1, vcc
	v_add_u32_e32 v216, s57, v214
	v_cmp_le_i32_e32 vcc, v161, v216
	s_nop 1
	v_cndmask_b32_e64 v168, 0, -1, vcc
	v_or_b32_e32 v217, 16, v161
	v_cmp_le_i32_e32 vcc, v217, v216
	s_nop 1
	v_cndmask_b32_e64 v169, 0, -1, vcc
	v_or_b32_e32 v218, 32, v161
	v_cmp_le_i32_e32 vcc, v218, v216
	s_nop 1
	v_cndmask_b32_e64 v170, 0, -1, vcc
	v_add_u32_e32 v219, 13, v161
	v_cmp_lt_i32_e32 vcc, v219, v216
	s_nop 1
	v_cndmask_b32_e64 v171, 0, -1, vcc
	v_add_u32_e32 v220, 14, v161
	v_cmp_lt_i32_e32 vcc, v220, v216
	s_nop 1
	v_cndmask_b32_e64 v172, 0, -1, vcc
	v_lshlrev_b32_e32 v213, 2, v162
	v_add_u32_e32 v214, 16, v213
	v_cndmask_b32_e64 v215, 1, 0, s[20:21]
	v_or_b32_e32 v216, s57, v161
	v_add_u32_e32 v217, v215, v216
	v_cmp_lt_i32_e32 vcc, v214, v217
	s_nop 1
	v_cndmask_b32_e64 v173, 0, -1, vcc
	v_add_u32_e32 v218, 17, v213
	v_cmp_lt_i32_e32 vcc, v218, v217
	s_nop 1
	v_cndmask_b32_e64 v174, 0, -1, vcc
	v_add_u32_e32 v219, 18, v213
	v_cmp_lt_i32_e32 vcc, v219, v217
	s_nop 1
	v_cndmask_b32_e64 v175, 0, -1, vcc
	v_or_b32_e32 v220, s60, v161
	v_add_u32_e32 v221, v215, v220
	v_cmp_lt_i32_e32 vcc, v219, v221
	s_nop 1
	v_cndmask_b32_e64 v176, 0, -1, vcc
	v_lshlrev_b32_e32 v213, 2, v162
	v_add_u32_e32 v214, 19, v213
	v_cndmask_b32_e64 v215, 1, 0, s[20:21]
	v_or_b32_e32 v216, s57, v161
	v_add_u32_e32 v217, v215, v216
	v_cmp_lt_i32_e32 vcc, v214, v217
	s_nop 1
	v_cndmask_b32_e64 v177, 0, -1, vcc
	v_or_b32_e32 v218, s60, v161
	v_add_u32_e32 v219, v215, v218
	v_cmp_lt_i32_e32 vcc, v214, v219
	s_nop 1
	v_cndmask_b32_e64 v178, 0, -1, vcc
	v_add_u32_e32 v220, 29, v161
	v_add_u32_e32 v221, s57, v213
	v_cmp_lt_i32_e32 vcc, v220, v221
	s_nop 1
	v_cndmask_b32_e64 v179, 0, -1, vcc
	v_add_u32_e32 v213, 30, v161
	v_lshlrev_b32_e32 v214, 2, v162
	v_add_u32_e32 v215, s57, v214
	v_cmp_lt_i32_e32 vcc, v213, v215
	s_nop 1
	v_cndmask_b32_e64 v180, 0, -1, vcc
	v_add_u32_e32 v216, 32, v214
	v_cndmask_b32_e64 v217, 1, 0, s[20:21]
	v_or_b32_e32 v218, s57, v161
	v_add_u32_e32 v219, v217, v218
	v_cmp_lt_i32_e32 vcc, v216, v219
	s_nop 1
	v_cndmask_b32_e64 v181, 0, -1, vcc
	v_or_b32_e32 v220, s60, v161
	v_add_u32_e32 v221, v217, v220
	v_cmp_lt_i32_e32 vcc, v216, v221
	s_nop 1
	v_cndmask_b32_e64 v182, 0, -1, vcc
	v_lshlrev_b32_e32 v213, 2, v162
	v_add_u32_e32 v214, 33, v213
	v_cndmask_b32_e64 v215, 1, 0, s[20:21]
	v_or_b32_e32 v216, s57, v161
	v_add_u32_e32 v217, v215, v216
	v_cmp_lt_i32_e32 vcc, v214, v217
	s_nop 1
	v_cndmask_b32_e64 v183, 0, -1, vcc
	v_or_b32_e32 v218, s60, v161
	v_add_u32_e32 v219, v215, v218
	v_cmp_lt_i32_e32 vcc, v214, v219
	s_nop 1
	v_cndmask_b32_e64 v184, 0, -1, vcc
	v_add_u32_e32 v220, 34, v213
	v_cmp_lt_i32_e32 vcc, v220, v217
	s_nop 1
	v_cndmask_b32_e64 v185, 0, -1, vcc
	v_lshlrev_b32_e32 v213, 2, v162
	v_add_u32_e32 v214, 34, v213
	v_cndmask_b32_e64 v215, 1, 0, s[20:21]
	v_or_b32_e32 v216, s60, v161
	v_add_u32_e32 v217, v215, v216
	v_cmp_lt_i32_e32 vcc, v214, v217
	s_nop 1
	v_cndmask_b32_e64 v186, 0, -1, vcc
	v_add_u32_e32 v218, 35, v213
	v_or_b32_e32 v219, s57, v161
	v_add_u32_e32 v220, v215, v219
	v_cmp_lt_i32_e32 vcc, v218, v220
	s_nop 1
	v_cndmask_b32_e64 v187, 0, -1, vcc
	v_lshlrev_b32_e32 v213, 2, v162
	v_add_u32_e32 v214, 35, v213
	v_cndmask_b32_e64 v215, 1, 0, s[20:21]
	v_or_b32_e32 v216, s60, v161
	v_add_u32_e32 v217, v215, v216
	v_cmp_lt_i32_e32 vcc, v214, v217
	s_nop 1
	v_cndmask_b32_e64 v188, 0, -1, vcc
	v_add_u32_e32 v218, 48, v213
	v_cmp_lt_i32_e32 vcc, v218, v217
	s_nop 1
	v_cndmask_b32_e64 v189, 0, -1, vcc
	v_add_u32_e32 v219, 49, v213
	v_cmp_lt_i32_e32 vcc, v219, v217
	s_nop 1
	v_cndmask_b32_e64 v190, 0, -1, vcc
	v_add_u32_e32 v220, 50, v213
	v_cmp_lt_i32_e32 vcc, v220, v217
	s_nop 1
	v_cndmask_b32_e64 v191, 0, -1, vcc
	v_lshlrev_b32_e32 v213, 2, v162
	v_add_u32_e32 v214, 51, v213
	v_cndmask_b32_e64 v215, 1, 0, s[20:21]
	v_or_b32_e32 v216, s60, v161
	v_add_u32_e32 v217, v215, v216
	v_cmp_lt_i32_e32 vcc, v214, v217
	s_nop 1
	v_cndmask_b32_e64 v192, 0, -1, vcc
	v_add_u32_e32 v218, s57, v213
	v_cmp_lt_i32_e32 vcc, v161, v218
	s_nop 1
	v_cndmask_b32_e64 v193, 0, -1, vcc
	v_or_b32_e32 v219, 2, v218
	v_cmp_lt_i32_e32 vcc, v161, v219
	s_nop 1
	v_cndmask_b32_e64 v194, 0, -1, vcc
	v_or_b32_e32 v220, 3, v218
	v_cmp_lt_i32_e32 vcc, v161, v220
	s_nop 1
	v_cndmask_b32_e64 v195, 0, -1, vcc
	v_lshlrev_b32_e32 v213, 2, v162
	v_cndmask_b32_e64 v214, 1, 0, s[20:21]
	v_or_b32_e32 v215, s57, v161
	v_add_u32_e32 v216, v214, v215
	v_cmp_lt_i32_e32 vcc, v213, v216
	s_nop 1
	v_cndmask_b32_e64 v196, 0, -1, vcc
	v_or_b32_e32 v217, s60, v161
	v_add_u32_e32 v218, v214, v217
	v_cmp_lt_i32_e32 vcc, v213, v218
	s_nop 1
	v_cndmask_b32_e64 v197, 0, -1, vcc
	v_or_b32_e32 v219, 16, v161
	v_add_u32_e32 v220, s57, v213
	v_cmp_lt_i32_e32 vcc, v219, v220
	s_nop 1
	v_cndmask_b32_e64 v198, 0, -1, vcc
	v_lshlrev_b32_e32 v213, 2, v162
	v_or_b32_e32 v214, 2, v213
	v_cndmask_b32_e64 v215, 1, 0, s[20:21]
	v_or_b32_e32 v216, s57, v161
	v_add_u32_e32 v217, v215, v216
	v_cmp_lt_i32_e32 vcc, v214, v217
	s_nop 1
	v_cndmask_b32_e64 v199, 0, -1, vcc
	v_or_b32_e32 v218, s60, v161
	v_add_u32_e32 v219, v215, v218
	v_cmp_lt_i32_e32 vcc, v214, v219
	s_nop 1
	v_cndmask_b32_e64 v200, 0, -1, vcc
	v_or_b32_e32 v220, 32, v161
	v_add_u32_e32 v221, s57, v213
	v_cmp_lt_i32_e32 vcc, v220, v221
	s_nop 1
	v_cndmask_b32_e64 v201, 0, -1, vcc
	v_lshlrev_b32_e32 v213, 2, v162
	v_or_b32_e32 v214, 3, v213
	v_cndmask_b32_e64 v215, 1, 0, s[20:21]
	v_or_b32_e32 v216, s57, v161
	v_add_u32_e32 v217, v215, v216
	v_cmp_lt_i32_e32 vcc, v214, v217
	s_nop 1
	v_cndmask_b32_e64 v202, 0, -1, vcc
	v_or_b32_e32 v218, s60, v161
	v_add_u32_e32 v219, v215, v218
	v_cmp_lt_i32_e32 vcc, v214, v219
	s_nop 1
	v_cndmask_b32_e64 v203, 0, -1, vcc
	v_mov_b32_e32 v220, v23
	v_lshl_add_u32 v204, v220, 1, s74
	s_movk_i32 s96, 0x500
	v_mul_lo_u32 v213, v162, s96
	v_cmp_gt_i32_e32 vcc, 2, v162
	s_nop 1
	v_cndmask_b32_e32 v214, v80, v81, vcc
	v_add3_u32 v215, 0, v213, v214
	v_mov_b32_e32 v205, v215
	v_mov_b32_e32 v206, s16
	v_mov_b32_e32 v207, v23
	v_mul_u32_u24_e32 v208, 0x90, v161
	v_or_b32_e32 v209, 16, v161
	v_or_b32_e32 v210, 32, v161
	v_or_b32_e32 v211, 48, v161
	s_mov_b32 s96, 0x5040100
	s_mov_b32 s97, 0x7060302
	s_branch .LBB0_664
